# grid barriers: wave 0 of every workgroup issues buffer_wbl2 sc1 on arrival (early L2 writeback before the leader's)
# baseline (speedup 1.0000x reference)
; __device__ __forceinline__ unsigned xb_ld(unsigned* p)              { return __hip_atomic_load(p, __ATOMIC_RELAXED, __HIP_MEMORY_SCOPE_AGENT); }
; __device__ __forceinline__ void xcd_barrier_complete(unsigned* bar, unsigned x, unsigned& nloc, unsigned& nx) {
;     const unsigned G = gridDim.x * gridDim.y * gridDim.z;
;     unsigned sum, cnt, mine, sp = 0u;
;     for (;;) {
;         sum = 0u; cnt = 0u; mine = 0u;
; #pragma unroll
;         for (unsigned j = 0; j < 16; ++j) { const unsigned c = xb_ld(&bar[XB_XCNT(j)]); sum += c; cnt += (c > 0u) ? 1u : 0u; mine = (j == x) ? c : mine; }
; __device__ __forceinline__ void xcd_barrier(const XcdBarrier& b) {
;     asm volatile("s_waitcnt vmcnt(0)" ::: "memory");
;     __syncthreads();
;     if (threadIdx.x == 0) {
;         unsigned* bar = b.bar;
;         __builtin_amdgcn_s_waitcnt(0);
;         unsigned nloc = b.st[0], nx = b.st[1];
;         if (nloc == 0u) { xcd_barrier_complete(bar, b.x, nloc, nx); b.st[0] = nloc; b.st[1] = nx; }
.LBB0_89:
	s_mov_b32 s6, s2
	s_mov_b64 s[4:5], s[0:1]
	s_nop 0
	v_mov_b64_e32 v[0:1], s[4:5]
	s_cmp_lg_u32 s3, 0
	s_cbranch_scc1 .Lwb_skip_1
	buffer_wbl2 sc1
.Lwb_skip_1:
	flat_load_dwordx2 v[0:1], v[0:1] offset:152
	s_getreg_b32 s4, hwreg(HW_REG_XCC_ID, 0, 4)
	s_waitcnt vmcnt(0)
	s_waitcnt lgkmcnt(0)
	s_barrier
	s_mov_b64 s[40:41], exec
	v_readlane_b32 s6, v254, 0
	v_readlane_b32 s7, v254, 1
	s_and_b64 s[6:7], s[40:41], s[6:7]
	s_mov_b64 exec, s[6:7]
	s_cbranch_execz .LBB0_133
	s_add_i32 s5, 0, 0x20020
	v_mov_b32_e32 v2, s5
	s_waitcnt vmcnt(0) expcnt(0) lgkmcnt(0)
	ds_read_b32 v6, v2
	s_add_i32 s5, 0, 0x20024
	v_mov_b32_e32 v2, s5
	ds_read_b32 v4, v2
	s_and_b32 s13, s4, 15
	s_waitcnt lgkmcnt(1)
	v_cmp_ne_u32_e32 vcc, 0, v6
	s_cbranch_vccnz .LBB0_104
	s_mov_b64 s[4:5], 0x28d00200
	v_lshl_add_u64 v[2:3], v[0:1], 0, s[4:5]
	s_mov_b64 s[4:5], 0x28d00400
	s_waitcnt lgkmcnt(0)
	v_lshl_add_u64 v[4:5], v[0:1], 0, s[4:5]
	s_mov_b64 s[4:5], 0x28d00500
	v_lshl_add_u64 v[6:7], v[0:1], 0, s[4:5]
	s_mov_b64 s[4:5], 0x28d00600
	v_lshl_add_u64 v[8:9], v[0:1], 0, s[4:5]
	s_mov_b64 s[4:5], 0x28d00700
	v_lshl_add_u64 v[10:11], v[0:1], 0, s[4:5]
	s_mov_b64 s[4:5], 0x28d00800
	v_lshl_add_u64 v[12:13], v[0:1], 0, s[4:5]
	s_mov_b64 s[4:5], 0x28d00900
	v_lshl_add_u64 v[14:15], v[0:1], 0, s[4:5]
	s_mov_b64 s[4:5], 0x28d00a00
	v_lshl_add_u64 v[16:17], v[0:1], 0, s[4:5]
	s_mov_b64 s[4:5], 0x28d00b00
	v_lshl_add_u64 v[18:19], v[0:1], 0, s[4:5]
	s_mov_b64 s[4:5], 0x28d00c00
	v_lshl_add_u64 v[20:21], v[0:1], 0, s[4:5]
	s_mov_b64 s[4:5], 0x28d00d00
	v_lshl_add_u64 v[22:23], v[0:1], 0, s[4:5]
	s_mov_b64 s[4:5], 0x28d00e00
	v_lshl_add_u64 v[24:25], v[0:1], 0, s[4:5]
	s_mov_b64 s[4:5], 0x28d00f00
	v_lshl_add_u64 v[26:27], v[0:1], 0, s[4:5]
	s_mov_b64 s[4:5], 0x28d01000
	v_lshl_add_u64 v[28:29], v[0:1], 0, s[4:5]
	s_mov_b64 s[4:5], 0x28d01100
	v_lshl_add_u64 v[30:31], v[0:1], 0, s[4:5]
	s_mov_b64 s[4:5], 0x28d01200
	s_mul_i32 s24, s39, s12
	v_lshl_add_u64 v[32:33], v[0:1], 0, s[4:5]
	s_mov_b64 s[4:5], 0x28d01300
	s_mul_i32 s24, s24, s38
	v_lshl_add_u64 v[34:35], v[0:1], 0, s[4:5]
	s_mov_b32 s25, 1
	s_mov_b64 s[4:5], 0
	s_branch .LBB0_94

; __device__ __forceinline__ unsigned xb_ld(unsigned* p)              { return __hip_atomic_load(p, __ATOMIC_RELAXED, __HIP_MEMORY_SCOPE_AGENT); }
; __device__ __forceinline__ void xcd_barrier_complete(unsigned* bar, unsigned x, unsigned& nloc, unsigned& nx) {
;     const unsigned G = gridDim.x * gridDim.y * gridDim.z;
;     unsigned sum, cnt, mine, sp = 0u;
;     for (;;) {
;         sum = 0u; cnt = 0u; mine = 0u;
; #pragma unroll
;         for (unsigned j = 0; j < 16; ++j) { const unsigned c = xb_ld(&bar[XB_XCNT(j)]); sum += c; cnt += (c > 0u) ? 1u : 0u; mine = (j == x) ? c : mine; }
; __device__ __forceinline__ void xcd_barrier(const XcdBarrier& b) {
;     asm volatile("s_waitcnt vmcnt(0)" ::: "memory");
;     __syncthreads();
;     if (threadIdx.x == 0) {
;         unsigned* bar = b.bar;
;         __builtin_amdgcn_s_waitcnt(0);
;         unsigned nloc = b.st[0], nx = b.st[1];
;         if (nloc == 0u) { xcd_barrier_complete(bar, b.x, nloc, nx); b.st[0] = nloc; b.st[1] = nx; }
.Lwb_skip_3:
	flat_load_dwordx2 v[0:1], v[0:1] offset:152
	s_getreg_b32 s4, hwreg(HW_REG_XCC_ID, 0, 4)
	s_waitcnt vmcnt(0)
	s_waitcnt lgkmcnt(0)
	s_barrier
	s_mov_b64 s[52:53], exec
	v_readlane_b32 s6, v254, 0
	v_readlane_b32 s7, v254, 1
	s_and_b64 s[6:7], s[52:53], s[6:7]
	s_mov_b64 exec, s[6:7]
	s_cbranch_execz .LBB0_323
	v_mov_b32_e32 v2, s54
	s_waitcnt vmcnt(0) expcnt(0) lgkmcnt(0)
	ds_read_b32 v6, v2
	v_mov_b32_e32 v2, s94
	ds_read_b32 v4, v2
	s_and_b32 s38, s4, 15
	s_waitcnt lgkmcnt(1)
	v_cmp_ne_u32_e32 vcc, 0, v6
	s_cbranch_vccnz .LBB0_294
	s_mov_b64 s[4:5], 0x28d00200
	v_lshl_add_u64 v[2:3], v[0:1], 0, s[4:5]
	s_mov_b64 s[4:5], 0x28d00400
	s_waitcnt lgkmcnt(0)
	v_lshl_add_u64 v[4:5], v[0:1], 0, s[4:5]
	s_mov_b64 s[4:5], 0x28d00500
	v_lshl_add_u64 v[6:7], v[0:1], 0, s[4:5]
	s_mov_b64 s[4:5], 0x28d00600
	v_lshl_add_u64 v[8:9], v[0:1], 0, s[4:5]
	s_mov_b64 s[4:5], 0x28d00700
	v_lshl_add_u64 v[10:11], v[0:1], 0, s[4:5]
	s_mov_b64 s[4:5], 0x28d00800
	v_lshl_add_u64 v[12:13], v[0:1], 0, s[4:5]
	s_mov_b64 s[4:5], 0x28d00900
	v_lshl_add_u64 v[14:15], v[0:1], 0, s[4:5]
	s_mov_b64 s[4:5], 0x28d00a00
	v_lshl_add_u64 v[16:17], v[0:1], 0, s[4:5]
	s_mov_b64 s[4:5], 0x28d00b00
	v_lshl_add_u64 v[18:19], v[0:1], 0, s[4:5]
	s_mov_b64 s[4:5], 0x28d00c00
	v_lshl_add_u64 v[20:21], v[0:1], 0, s[4:5]
	s_mov_b64 s[4:5], 0x28d00d00
	v_lshl_add_u64 v[22:23], v[0:1], 0, s[4:5]
	s_mov_b64 s[4:5], 0x28d00e00
	v_lshl_add_u64 v[24:25], v[0:1], 0, s[4:5]
	s_mov_b64 s[4:5], 0x28d00f00
	v_lshl_add_u64 v[26:27], v[0:1], 0, s[4:5]
	s_mov_b64 s[4:5], 0x28d01000
	v_lshl_add_u64 v[28:29], v[0:1], 0, s[4:5]
	s_mov_b64 s[4:5], 0x28d01100
	v_lshl_add_u64 v[30:31], v[0:1], 0, s[4:5]
	s_mov_b64 s[4:5], 0x28d01200
	v_lshl_add_u64 v[32:33], v[0:1], 0, s[4:5]
	s_mov_b64 s[4:5], 0x28d01300
	v_lshl_add_u64 v[34:35], v[0:1], 0, s[4:5]
	s_mov_b32 s24, 1
	s_mov_b64 s[4:5], 0
	s_branch .LBB0_284

; __device__ __forceinline__ unsigned xb_ld(unsigned* p)              { return __hip_atomic_load(p, __ATOMIC_RELAXED, __HIP_MEMORY_SCOPE_AGENT); }
; __device__ __forceinline__ void xcd_barrier_complete(unsigned* bar, unsigned x, unsigned& nloc, unsigned& nx) {
;     const unsigned G = gridDim.x * gridDim.y * gridDim.z;
;     unsigned sum, cnt, mine, sp = 0u;
;     for (;;) {
;         sum = 0u; cnt = 0u; mine = 0u;
; #pragma unroll
;         for (unsigned j = 0; j < 16; ++j) { const unsigned c = xb_ld(&bar[XB_XCNT(j)]); sum += c; cnt += (c > 0u) ? 1u : 0u; mine = (j == x) ? c : mine; }
; __device__ __forceinline__ void xcd_barrier(const XcdBarrier& b) {
;     asm volatile("s_waitcnt vmcnt(0)" ::: "memory");
;     __syncthreads();
;     if (threadIdx.x == 0) {
;         unsigned* bar = b.bar;
;         __builtin_amdgcn_s_waitcnt(0);
;         unsigned nloc = b.st[0], nx = b.st[1];
;         if (nloc == 0u) { xcd_barrier_complete(bar, b.x, nloc, nx); b.st[0] = nloc; b.st[1] = nx; }
.LBB0_369:
	s_mov_b64 s[4:5], s[0:1]
	s_mov_b32 s6, s2
	s_nop 0
	v_mov_b64_e32 v[0:1], s[4:5]
	s_cmp_lg_u32 s3, 0
	s_cbranch_scc1 .Lwb_skip_4
	buffer_wbl2 sc1
.Lwb_skip_4:
	flat_load_dwordx2 v[0:1], v[0:1] offset:152
	s_getreg_b32 s4, hwreg(HW_REG_XCC_ID, 0, 4)
	s_waitcnt vmcnt(0)
	s_waitcnt vmcnt(0) lgkmcnt(0)
	s_barrier
	s_mov_b64 s[52:53], exec
	v_readlane_b32 s6, v254, 0
	v_readlane_b32 s7, v254, 1
	s_and_b64 s[6:7], s[52:53], s[6:7]
	s_mov_b64 exec, s[6:7]
	s_cbranch_execz .LBB0_413
	v_mov_b32_e32 v2, s54
	s_waitcnt vmcnt(0) expcnt(0) lgkmcnt(0)
	ds_read_b32 v6, v2
	v_mov_b32_e32 v2, s94
	ds_read_b32 v4, v2
	s_and_b32 s38, s4, 15
	s_waitcnt lgkmcnt(1)
	v_cmp_ne_u32_e32 vcc, 0, v6
	s_cbranch_vccnz .LBB0_384
	s_mov_b64 s[4:5], 0x28d00200
	v_lshl_add_u64 v[2:3], v[0:1], 0, s[4:5]
	s_mov_b64 s[4:5], 0x28d00400
	s_waitcnt lgkmcnt(0)
	v_lshl_add_u64 v[4:5], v[0:1], 0, s[4:5]
	s_mov_b64 s[4:5], 0x28d00500
	v_lshl_add_u64 v[6:7], v[0:1], 0, s[4:5]
	s_mov_b64 s[4:5], 0x28d00600
	v_lshl_add_u64 v[8:9], v[0:1], 0, s[4:5]
	s_mov_b64 s[4:5], 0x28d00700
	v_lshl_add_u64 v[10:11], v[0:1], 0, s[4:5]
	s_mov_b64 s[4:5], 0x28d00800
	v_lshl_add_u64 v[12:13], v[0:1], 0, s[4:5]
	s_mov_b64 s[4:5], 0x28d00900
	v_lshl_add_u64 v[14:15], v[0:1], 0, s[4:5]
	s_mov_b64 s[4:5], 0x28d00a00
	v_lshl_add_u64 v[16:17], v[0:1], 0, s[4:5]
	s_mov_b64 s[4:5], 0x28d00b00
	v_lshl_add_u64 v[18:19], v[0:1], 0, s[4:5]
	s_mov_b64 s[4:5], 0x28d00c00
	v_lshl_add_u64 v[20:21], v[0:1], 0, s[4:5]
	s_mov_b64 s[4:5], 0x28d00d00
	v_lshl_add_u64 v[22:23], v[0:1], 0, s[4:5]
	s_mov_b64 s[4:5], 0x28d00e00
	v_lshl_add_u64 v[24:25], v[0:1], 0, s[4:5]
	s_mov_b64 s[4:5], 0x28d00f00
	v_lshl_add_u64 v[26:27], v[0:1], 0, s[4:5]
	s_mov_b64 s[4:5], 0x28d01000
	v_lshl_add_u64 v[28:29], v[0:1], 0, s[4:5]
	s_mov_b64 s[4:5], 0x28d01100
	v_lshl_add_u64 v[30:31], v[0:1], 0, s[4:5]
	s_mov_b64 s[4:5], 0x28d01200
	v_lshl_add_u64 v[32:33], v[0:1], 0, s[4:5]
	s_mov_b64 s[4:5], 0x28d01300
	v_lshl_add_u64 v[34:35], v[0:1], 0, s[4:5]
	s_mov_b32 s24, 1
	s_mov_b64 s[4:5], 0
	s_branch .LBB0_374

; __device__ __forceinline__ unsigned xb_ld(unsigned* p)              { return __hip_atomic_load(p, __ATOMIC_RELAXED, __HIP_MEMORY_SCOPE_AGENT); }
; __device__ __forceinline__ void xcd_barrier_complete(unsigned* bar, unsigned x, unsigned& nloc, unsigned& nx) {
;     const unsigned G = gridDim.x * gridDim.y * gridDim.z;
;     unsigned sum, cnt, mine, sp = 0u;
;     for (;;) {
;         sum = 0u; cnt = 0u; mine = 0u;
; #pragma unroll
;         for (unsigned j = 0; j < 16; ++j) { const unsigned c = xb_ld(&bar[XB_XCNT(j)]); sum += c; cnt += (c > 0u) ? 1u : 0u; mine = (j == x) ? c : mine; }
; __device__ __forceinline__ void xcd_barrier(const XcdBarrier& b) {
;     asm volatile("s_waitcnt vmcnt(0)" ::: "memory");
;     __syncthreads();
;     if (threadIdx.x == 0) {
;         unsigned* bar = b.bar;
;         __builtin_amdgcn_s_waitcnt(0);
;         unsigned nloc = b.st[0], nx = b.st[1];
;         if (nloc == 0u) { xcd_barrier_complete(bar, b.x, nloc, nx); b.st[0] = nloc; b.st[1] = nx; }
.Lwb_skip_5:
	flat_load_dwordx2 v[0:1], v[0:1] offset:152
	s_getreg_b32 s4, hwreg(HW_REG_XCC_ID, 0, 4)
	s_waitcnt vmcnt(0)
	s_waitcnt lgkmcnt(0)
	s_barrier
	s_mov_b64 s[48:49], exec
	v_readlane_b32 s6, v254, 0
	v_readlane_b32 s7, v254, 1
	s_and_b64 s[6:7], s[48:49], s[6:7]
	s_mov_b64 exec, s[6:7]
	s_cbranch_execz .LBB0_474
	v_mov_b32_e32 v2, s13
	s_waitcnt vmcnt(0) expcnt(0) lgkmcnt(0)
	ds_read_b32 v6, v2
	v_mov_b32_e32 v2, s94
	ds_read_b32 v4, v2
	s_and_b32 s38, s4, 15
	s_waitcnt lgkmcnt(1)
	v_cmp_ne_u32_e32 vcc, 0, v6
	s_cbranch_vccnz .LBB0_445
	s_mov_b64 s[4:5], 0x28d00200
	v_lshl_add_u64 v[2:3], v[0:1], 0, s[4:5]
	s_mov_b64 s[4:5], 0x28d00400
	s_waitcnt lgkmcnt(0)
	v_lshl_add_u64 v[4:5], v[0:1], 0, s[4:5]
	s_mov_b64 s[4:5], 0x28d00500
	v_lshl_add_u64 v[6:7], v[0:1], 0, s[4:5]
	s_mov_b64 s[4:5], 0x28d00600
	v_lshl_add_u64 v[8:9], v[0:1], 0, s[4:5]
	s_mov_b64 s[4:5], 0x28d00700
	v_lshl_add_u64 v[10:11], v[0:1], 0, s[4:5]
	s_mov_b64 s[4:5], 0x28d00800
	v_lshl_add_u64 v[12:13], v[0:1], 0, s[4:5]
	s_mov_b64 s[4:5], 0x28d00900
	v_lshl_add_u64 v[14:15], v[0:1], 0, s[4:5]
	s_mov_b64 s[4:5], 0x28d00a00
	v_lshl_add_u64 v[16:17], v[0:1], 0, s[4:5]
	s_mov_b64 s[4:5], 0x28d00b00
	v_lshl_add_u64 v[18:19], v[0:1], 0, s[4:5]
	s_mov_b64 s[4:5], 0x28d00c00
	v_lshl_add_u64 v[20:21], v[0:1], 0, s[4:5]
	s_mov_b64 s[4:5], 0x28d00d00
	v_lshl_add_u64 v[22:23], v[0:1], 0, s[4:5]
	s_mov_b64 s[4:5], 0x28d00e00
	v_lshl_add_u64 v[24:25], v[0:1], 0, s[4:5]
	s_mov_b64 s[4:5], 0x28d00f00
	v_lshl_add_u64 v[26:27], v[0:1], 0, s[4:5]
	s_mov_b64 s[4:5], 0x28d01000
	v_lshl_add_u64 v[28:29], v[0:1], 0, s[4:5]
	s_mov_b64 s[4:5], 0x28d01100
	v_lshl_add_u64 v[30:31], v[0:1], 0, s[4:5]
	s_mov_b64 s[4:5], 0x28d01200
	v_lshl_add_u64 v[32:33], v[0:1], 0, s[4:5]
	s_mov_b64 s[4:5], 0x28d01300
	v_lshl_add_u64 v[34:35], v[0:1], 0, s[4:5]
	s_mov_b32 s24, 1
	s_mov_b64 s[4:5], 0
	s_branch .LBB0_435

; __device__ __forceinline__ unsigned xb_ld(unsigned* p)              { return __hip_atomic_load(p, __ATOMIC_RELAXED, __HIP_MEMORY_SCOPE_AGENT); }
; __device__ __forceinline__ void xcd_barrier_complete(unsigned* bar, unsigned x, unsigned& nloc, unsigned& nx) {
;     const unsigned G = gridDim.x * gridDim.y * gridDim.z;
;     unsigned sum, cnt, mine, sp = 0u;
;     for (;;) {
;         sum = 0u; cnt = 0u; mine = 0u;
; #pragma unroll
;         for (unsigned j = 0; j < 16; ++j) { const unsigned c = xb_ld(&bar[XB_XCNT(j)]); sum += c; cnt += (c > 0u) ? 1u : 0u; mine = (j == x) ? c : mine; }
; __device__ __forceinline__ void xcd_barrier(const XcdBarrier& b) {
;     asm volatile("s_waitcnt vmcnt(0)" ::: "memory");
;     __syncthreads();
;     if (threadIdx.x == 0) {
;         unsigned* bar = b.bar;
;         __builtin_amdgcn_s_waitcnt(0);
;         unsigned nloc = b.st[0], nx = b.st[1];
;         if (nloc == 0u) { xcd_barrier_complete(bar, b.x, nloc, nx); b.st[0] = nloc; b.st[1] = nx; }
.LBB0_534:
	s_mov_b32 s6, s2
	s_mov_b64 s[4:5], s[0:1]
	s_waitcnt vmcnt(0)
	v_mov_b64_e32 v[0:1], s[4:5]
	s_cmp_lg_u32 s3, 0
	s_cbranch_scc1 .Lwb_skip_6
	buffer_wbl2 sc1
.Lwb_skip_6:
	flat_load_dwordx2 v[0:1], v[0:1] offset:152
	s_getreg_b32 s4, hwreg(HW_REG_XCC_ID, 0, 4)
	s_waitcnt vmcnt(0)
	s_waitcnt lgkmcnt(0)
	s_barrier
	s_mov_b64 s[48:49], exec
	v_readlane_b32 s6, v254, 0
	v_readlane_b32 s7, v254, 1
	s_and_b64 s[6:7], s[48:49], s[6:7]
	s_mov_b64 exec, s[6:7]
	s_cbranch_execz .LBB0_578
	v_mov_b32_e32 v2, s54
	s_waitcnt vmcnt(0) expcnt(0) lgkmcnt(0)
	ds_read_b32 v6, v2
	v_mov_b32_e32 v2, s94
	ds_read_b32 v4, v2
	s_and_b32 s38, s4, 15
	s_waitcnt lgkmcnt(1)
	v_cmp_ne_u32_e32 vcc, 0, v6
	s_cbranch_vccnz .LBB0_549
	s_mov_b64 s[4:5], 0x28d00200
	v_lshl_add_u64 v[2:3], v[0:1], 0, s[4:5]
	s_mov_b64 s[4:5], 0x28d00400
	s_waitcnt lgkmcnt(0)
	v_lshl_add_u64 v[4:5], v[0:1], 0, s[4:5]
	s_mov_b64 s[4:5], 0x28d00500
	v_lshl_add_u64 v[6:7], v[0:1], 0, s[4:5]
	s_mov_b64 s[4:5], 0x28d00600
	v_lshl_add_u64 v[8:9], v[0:1], 0, s[4:5]
	s_mov_b64 s[4:5], 0x28d00700
	v_lshl_add_u64 v[10:11], v[0:1], 0, s[4:5]
	s_mov_b64 s[4:5], 0x28d00800
	v_lshl_add_u64 v[12:13], v[0:1], 0, s[4:5]
	s_mov_b64 s[4:5], 0x28d00900
	v_lshl_add_u64 v[14:15], v[0:1], 0, s[4:5]
	s_mov_b64 s[4:5], 0x28d00a00
	v_lshl_add_u64 v[16:17], v[0:1], 0, s[4:5]
	s_mov_b64 s[4:5], 0x28d00b00
	v_lshl_add_u64 v[18:19], v[0:1], 0, s[4:5]
	s_mov_b64 s[4:5], 0x28d00c00
	v_lshl_add_u64 v[20:21], v[0:1], 0, s[4:5]
	s_mov_b64 s[4:5], 0x28d00d00
	v_lshl_add_u64 v[22:23], v[0:1], 0, s[4:5]
	s_mov_b64 s[4:5], 0x28d00e00
	v_lshl_add_u64 v[24:25], v[0:1], 0, s[4:5]
	s_mov_b64 s[4:5], 0x28d00f00
	v_lshl_add_u64 v[26:27], v[0:1], 0, s[4:5]
	s_mov_b64 s[4:5], 0x28d01000
	v_lshl_add_u64 v[28:29], v[0:1], 0, s[4:5]
	s_mov_b64 s[4:5], 0x28d01100
	v_lshl_add_u64 v[30:31], v[0:1], 0, s[4:5]
	s_mov_b64 s[4:5], 0x28d01200
	v_lshl_add_u64 v[32:33], v[0:1], 0, s[4:5]
	s_mov_b64 s[4:5], 0x28d01300
	v_lshl_add_u64 v[34:35], v[0:1], 0, s[4:5]
	s_mov_b32 s24, 1
	s_mov_b64 s[4:5], 0
	s_branch .LBB0_539
